# phase E: wide branch epilogue with rotating store-data registers + LDS-resident gate quarter
# baseline (speedup 1.0000x reference)
; __device__ __forceinline__ float bflo(unsigned u) { return __uint_as_float(u << 16); }
; __device__ __forceinline__ float bfhi(unsigned u) { return __uint_as_float(u & 0xFFFF0000u); }
; __device__ __forceinline__ void phaseE(const Params& p, int layer) {
;     ...
;         char* mb = (char*)merged + ((size_t)(brow + wr * 64) * 2048 + bcol + wc * 32) * 2;
; #pragma unroll
;         for (int ai = 0; ai < 2; ai++)
; #pragma unroll
;           for (int bj = 0; bj < 2; bj++) {
; #pragma unroll
;             for (int mh = 0; mh < 2; mh++) {
;               uint4 g4[2]; uint2 old[2][2];
; #pragma unroll
;               for (int mm = 0; mm < 2; mm++) {
;                 const int m = mh * 2 + mm;
;                 g4[mm] = *(const uint4*)(gsb + ((ai * 2 + bj) * 4 + m) * 8192 + gs_lane);
;                 if (br) {
; #pragma unroll
;                   for (int n = 0; n < 2; n++)
;                     old[mm][n] = *(const uint2*)(mb + ((size_t)(ai * 128 + m * 16) * 2048 + bj * 128 + n * 16) * 2 + lane_m);
;                 }
;               }
; #pragma unroll
;               for (int mm = 0; mm < 2; mm++) {
;                 const int m = mh * 2 + mm;
;                 const unsigned gq[4] = {g4[mm].x, g4[mm].y, g4[mm].z, g4[mm].w};
; #pragma unroll
;                 for (int n = 0; n < 2; n++) {
;                   f32x4 v = acc[ai][bj][m][n];
;                   float o0 = bflo(gq[2 * n]) * v[0], o1 = bfhi(gq[2 * n]) * v[1], o2 = bflo(gq[2 * n + 1]) * v[2], o3 = bfhi(gq[2 * n + 1]) * v[3];
;                   char* mp = mb + ((size_t)(ai * 128 + m * 16) * 2048 + bj * 128 + n * 16) * 2 + lane_m;
;                   if (br) { o0 += bflo(old[mm][n].x); o1 += bfhi(old[mm][n].x); o2 += bflo(old[mm][n].y); o3 += bfhi(old[mm][n].y); }
;                   *(uint2*)mp = make_uint2(pk2(o0, o1), pk2(o2, o3));
;                 }
;               }
.LBB0_2323:
	v_readlane_b32 s0, v253, 51
	v_readlane_b32 s1, v253, 52
	v_add_u32_e32 v165, 0x20000, v160
	v_and_b32_e32 v163, 63, v162
	v_add_u32_e32 v163, v163, v162
	s_cmp_lg_u64 s[12:13], 0
	s_nop 3
	s_cbranch_scc0 .Lbrepi_first
	ds_read_b128 v[128:131], v165
	global_load_dwordx4 v[132:135], v163, s[6:7]
	ds_read_b128 v[136:139], v165 offset:8192
	v_add_u32_e32 v210, 0x10000, v163
	global_load_dwordx4 v[140:143], v210, s[6:7]
	ds_read_b128 v[148:151], v165 offset:16384
	v_add_u32_e32 v211, 0x20000, v163
	global_load_dwordx4 v[152:155], v211, s[6:7]
	ds_read_b128 v[164:167], v165 offset:24576
	v_add_u32_e32 v210, 0x30000, v163
	global_load_dwordx4 v[168:171], v210, s[6:7]
	v_add_u32_e32 v146, 0x8000, v160
	global_load_dwordx4 v[172:175], v146, s[0:1]
	global_load_dwordx4 v[176:179], v163, s[6:7] offset:256
	v_add_u32_e32 v147, 0xa000, v160
	global_load_dwordx4 v[180:183], v147, s[0:1]
	v_add_u32_e32 v211, 0x10000, v163
	global_load_dwordx4 v[184:187], v211, s[6:7] offset:256
	v_add_u32_e32 v146, 0xc000, v160
	global_load_dwordx4 v[188:191], v146, s[0:1]
	v_add_u32_e32 v210, 0x20000, v163
	global_load_dwordx4 v[192:195], v210, s[6:7] offset:256
	v_add_u32_e32 v147, 0xe000, v160
	global_load_dwordx4 v[212:215], v147, s[0:1]
	v_add_u32_e32 v211, 0x30000, v163
	global_load_dwordx4 v[216:219], v211, s[6:7] offset:256
	v_add_u32_e32 v146, 0x10000, v160
	global_load_dwordx4 v[220:223], v146, s[0:1]
	v_add_u32_e32 v210, 0x80000, v163
	global_load_dwordx4 v[224:227], v210, s[6:7]
	s_waitcnt vmcnt(13) lgkmcnt(0)
	s_nop 3
	v_permlane16_swap_b32_e32 v132, v134
	v_permlane16_swap_b32_e32 v133, v135
	s_nop 3
	v_permlane32_swap_b32_e32 v132, v134
	v_permlane32_swap_b32_e32 v133, v135
	s_nop 3
	v_lshlrev_b32_e32 v156, 16, v128
	v_and_b32_e32 v157, 0xffff0000, v128
	v_lshlrev_b32_e32 v158, 16, v129
	v_and_b32_e32 v159, 0xffff0000, v129
	v_pk_mul_f32 v[156:157], v[124:125], v[156:157]
	v_pk_mul_f32 v[158:159], v[126:127], v[158:159]
	v_lshlrev_b32_e32 v244, 16, v130
	v_and_b32_e32 v245, 0xffff0000, v130
	v_lshlrev_b32_e32 v246, 16, v131
	v_and_b32_e32 v247, 0xffff0000, v131
	v_pk_mul_f32 v[244:245], v[120:121], v[244:245]
	v_pk_mul_f32 v[246:247], v[122:123], v[246:247]
	v_lshlrev_b32_e32 v196, 16, v132
	v_and_b32_e32 v197, 0xffff0000, v132
	v_lshlrev_b32_e32 v198, 16, v133
	v_and_b32_e32 v199, 0xffff0000, v133
	v_pk_add_f32 v[156:157], v[156:157], v[196:197]
	v_pk_add_f32 v[158:159], v[158:159], v[198:199]
	v_lshlrev_b32_e32 v200, 16, v134
	v_and_b32_e32 v201, 0xffff0000, v134
	v_lshlrev_b32_e32 v204, 16, v135
	v_and_b32_e32 v205, 0xffff0000, v135
	v_pk_add_f32 v[244:245], v[244:245], v[200:201]
	v_pk_add_f32 v[246:247], v[246:247], v[204:205]
	v_cvt_pk_bf16_f32 v228, v156, v157
	v_cvt_pk_bf16_f32 v229, v158, v159
	v_cvt_pk_bf16_f32 v230, v244, v245
	v_cvt_pk_bf16_f32 v231, v246, v247
	s_nop 3
	v_permlane32_swap_b32_e32 v228, v230
	v_permlane32_swap_b32_e32 v229, v231
	s_nop 3
	v_permlane16_swap_b32_e32 v228, v230
	v_permlane16_swap_b32_e32 v229, v231
	s_nop 3
	global_store_dwordx4 v163, v[228:231], s[6:7]
	v_add_u32_e32 v147, 0x12000, v160
	global_load_dwordx4 v[128:131], v147, s[0:1]
	v_add_u32_e32 v211, 0x90000, v163
	global_load_dwordx4 v[132:135], v211, s[6:7]
	s_waitcnt vmcnt(15) lgkmcnt(0)
	s_nop 3
	v_permlane16_swap_b32_e32 v140, v142
	v_permlane16_swap_b32_e32 v141, v143
	s_nop 3
	v_permlane32_swap_b32_e32 v140, v142
	v_permlane32_swap_b32_e32 v141, v143
	s_nop 3
	v_lshlrev_b32_e32 v156, 16, v136
	v_and_b32_e32 v157, 0xffff0000, v136
	v_lshlrev_b32_e32 v158, 16, v137
	v_and_b32_e32 v159, 0xffff0000, v137
	v_pk_mul_f32 v[156:157], v[116:117], v[156:157]
	v_pk_mul_f32 v[158:159], v[118:119], v[158:159]
	v_lshlrev_b32_e32 v244, 16, v138
	v_and_b32_e32 v245, 0xffff0000, v138
	v_lshlrev_b32_e32 v246, 16, v139
	v_and_b32_e32 v247, 0xffff0000, v139
	v_pk_mul_f32 v[244:245], v[112:113], v[244:245]
	v_pk_mul_f32 v[246:247], v[114:115], v[246:247]
	v_lshlrev_b32_e32 v196, 16, v140
	v_and_b32_e32 v197, 0xffff0000, v140
	v_lshlrev_b32_e32 v198, 16, v141
	v_and_b32_e32 v199, 0xffff0000, v141
	v_pk_add_f32 v[156:157], v[156:157], v[196:197]
	v_pk_add_f32 v[158:159], v[158:159], v[198:199]
	v_lshlrev_b32_e32 v200, 16, v142
	v_and_b32_e32 v201, 0xffff0000, v142
	v_lshlrev_b32_e32 v204, 16, v143
	v_and_b32_e32 v205, 0xffff0000, v143
	v_pk_add_f32 v[244:245], v[244:245], v[200:201]
	v_pk_add_f32 v[246:247], v[246:247], v[204:205]
	v_cvt_pk_bf16_f32 v232, v156, v157
	v_cvt_pk_bf16_f32 v233, v158, v159
	v_cvt_pk_bf16_f32 v234, v244, v245
	v_cvt_pk_bf16_f32 v235, v246, v247
	v_add_u32_e32 v210, 0x10000, v163
	s_nop 3
	v_permlane32_swap_b32_e32 v232, v234
	v_permlane32_swap_b32_e32 v233, v235
	s_nop 3
	v_permlane16_swap_b32_e32 v232, v234
	v_permlane16_swap_b32_e32 v233, v235
	s_nop 3
	global_store_dwordx4 v210, v[232:235], s[6:7]
	v_add_u32_e32 v146, 0x14000, v160
	global_load_dwordx4 v[136:139], v146, s[0:1]
	v_add_u32_e32 v211, 0xa0000, v163
	global_load_dwordx4 v[140:143], v211, s[6:7]
	s_waitcnt vmcnt(17) lgkmcnt(0)
; __device__ __forceinline__ float bflo(unsigned u) { return __uint_as_float(u << 16); }
; __device__ __forceinline__ float bfhi(unsigned u) { return __uint_as_float(u & 0xFFFF0000u); }
; __device__ __forceinline__ void phaseE(const Params& p, int layer) {
;     ...
;               uint4 g4[2]; uint2 old[2][2];
; #pragma unroll
;               for (int mm = 0; mm < 2; mm++) {
;                 const int m = mh * 2 + mm;
;                 g4[mm] = *(const uint4*)(gsb + ((ai * 2 + bj) * 4 + m) * 8192 + gs_lane);
;                 if (br) {
; #pragma unroll
;                   for (int n = 0; n < 2; n++)
;                     old[mm][n] = *(const uint2*)(mb + ((size_t)(ai * 128 + m * 16) * 2048 + bj * 128 + n * 16) * 2 + lane_m);
;                 }
;               }
; #pragma unroll
;               for (int mm = 0; mm < 2; mm++) {
;                 const int m = mh * 2 + mm;
;                 const unsigned gq[4] = {g4[mm].x, g4[mm].y, g4[mm].z, g4[mm].w};
; #pragma unroll
;                 for (int n = 0; n < 2; n++) {
;                   f32x4 v = acc[ai][bj][m][n];
;                   float o0 = bflo(gq[2 * n]) * v[0], o1 = bfhi(gq[2 * n]) * v[1], o2 = bflo(gq[2 * n + 1]) * v[2], o3 = bfhi(gq[2 * n + 1]) * v[3];
;                   char* mp = mb + ((size_t)(ai * 128 + m * 16) * 2048 + bj * 128 + n * 16) * 2 + lane_m;
;                   if (br) { o0 += bflo(old[mm][n].x); o1 += bfhi(old[mm][n].x); o2 += bflo(old[mm][n].y); o3 += bfhi(old[mm][n].y); }
;                   *(uint2*)mp = make_uint2(pk2(o0, o1), pk2(o2, o3));
;                 }
;               }
	s_nop 3
	v_permlane16_swap_b32_e32 v152, v154
	v_permlane16_swap_b32_e32 v153, v155
	s_nop 3
	v_permlane32_swap_b32_e32 v152, v154
	v_permlane32_swap_b32_e32 v153, v155
	s_nop 3
	v_lshlrev_b32_e32 v156, 16, v148
	v_and_b32_e32 v157, 0xffff0000, v148
	v_lshlrev_b32_e32 v158, 16, v149
	v_and_b32_e32 v159, 0xffff0000, v149
	v_pk_mul_f32 v[156:157], v[108:109], v[156:157]
	v_pk_mul_f32 v[158:159], v[110:111], v[158:159]
	v_lshlrev_b32_e32 v244, 16, v150
	v_and_b32_e32 v245, 0xffff0000, v150
	v_lshlrev_b32_e32 v246, 16, v151
	v_and_b32_e32 v247, 0xffff0000, v151
	v_pk_mul_f32 v[244:245], v[104:105], v[244:245]
	v_pk_mul_f32 v[246:247], v[106:107], v[246:247]
	v_lshlrev_b32_e32 v196, 16, v152
	v_and_b32_e32 v197, 0xffff0000, v152
	v_lshlrev_b32_e32 v198, 16, v153
	v_and_b32_e32 v199, 0xffff0000, v153
	v_pk_add_f32 v[156:157], v[156:157], v[196:197]
	v_pk_add_f32 v[158:159], v[158:159], v[198:199]
	v_lshlrev_b32_e32 v200, 16, v154
	v_and_b32_e32 v201, 0xffff0000, v154
	v_lshlrev_b32_e32 v204, 16, v155
	v_and_b32_e32 v205, 0xffff0000, v155
	v_pk_add_f32 v[244:245], v[244:245], v[200:201]
	v_pk_add_f32 v[246:247], v[246:247], v[204:205]
	v_cvt_pk_bf16_f32 v236, v156, v157
	v_cvt_pk_bf16_f32 v237, v158, v159
	v_cvt_pk_bf16_f32 v238, v244, v245
	v_cvt_pk_bf16_f32 v239, v246, v247
	v_add_u32_e32 v210, 0x20000, v163
	s_nop 3
	v_permlane32_swap_b32_e32 v236, v238
	v_permlane32_swap_b32_e32 v237, v239
	s_nop 3
	v_permlane16_swap_b32_e32 v236, v238
	v_permlane16_swap_b32_e32 v237, v239
	s_nop 3
	global_store_dwordx4 v210, v[236:239], s[6:7]
	v_add_u32_e32 v147, 0x16000, v160
	global_load_dwordx4 v[148:151], v147, s[0:1]
	v_add_u32_e32 v211, 0xb0000, v163
	global_load_dwordx4 v[152:155], v211, s[6:7]
	s_waitcnt vmcnt(19) lgkmcnt(0)
	s_nop 3
	v_permlane16_swap_b32_e32 v168, v170
	v_permlane16_swap_b32_e32 v169, v171
	s_nop 3
	v_permlane32_swap_b32_e32 v168, v170
	v_permlane32_swap_b32_e32 v169, v171
	s_nop 3
	v_lshlrev_b32_e32 v156, 16, v164
	v_and_b32_e32 v157, 0xffff0000, v164
	v_lshlrev_b32_e32 v158, 16, v165
	v_and_b32_e32 v159, 0xffff0000, v165
	v_pk_mul_f32 v[156:157], v[100:101], v[156:157]
	v_pk_mul_f32 v[158:159], v[102:103], v[158:159]
	v_lshlrev_b32_e32 v244, 16, v166
	v_and_b32_e32 v245, 0xffff0000, v166
	v_lshlrev_b32_e32 v246, 16, v167
	v_and_b32_e32 v247, 0xffff0000, v167
	v_pk_mul_f32 v[244:245], v[96:97], v[244:245]
	v_pk_mul_f32 v[246:247], v[98:99], v[246:247]
	v_lshlrev_b32_e32 v196, 16, v168
	v_and_b32_e32 v197, 0xffff0000, v168
	v_lshlrev_b32_e32 v198, 16, v169
	v_and_b32_e32 v199, 0xffff0000, v169
	v_pk_add_f32 v[156:157], v[156:157], v[196:197]
	v_pk_add_f32 v[158:159], v[158:159], v[198:199]
	v_lshlrev_b32_e32 v200, 16, v170
	v_and_b32_e32 v201, 0xffff0000, v170
	v_lshlrev_b32_e32 v204, 16, v171
	v_and_b32_e32 v205, 0xffff0000, v171
	v_pk_add_f32 v[244:245], v[244:245], v[200:201]
	v_pk_add_f32 v[246:247], v[246:247], v[204:205]
	v_cvt_pk_bf16_f32 v240, v156, v157
	v_cvt_pk_bf16_f32 v241, v158, v159
	v_cvt_pk_bf16_f32 v242, v244, v245
	v_cvt_pk_bf16_f32 v243, v246, v247
	v_add_u32_e32 v210, 0x30000, v163
	s_nop 3
	v_permlane32_swap_b32_e32 v240, v242
	v_permlane32_swap_b32_e32 v241, v243
	s_nop 3
	v_permlane16_swap_b32_e32 v240, v242
	v_permlane16_swap_b32_e32 v241, v243
	s_nop 3
	global_store_dwordx4 v210, v[240:243], s[6:7]
	v_add_u32_e32 v146, 0x18000, v160
	global_load_dwordx4 v[164:167], v146, s[0:1]
	v_add_u32_e32 v211, 0x80000, v163
	global_load_dwordx4 v[168:171], v211, s[6:7] offset:256
	s_waitcnt vmcnt(20)
	s_nop 3
	v_permlane16_swap_b32_e32 v176, v178
	v_permlane16_swap_b32_e32 v177, v179
	s_nop 3
	v_permlane32_swap_b32_e32 v176, v178
	v_permlane32_swap_b32_e32 v177, v179
	s_nop 3
	v_lshlrev_b32_e32 v156, 16, v172
	v_and_b32_e32 v157, 0xffff0000, v172
	v_lshlrev_b32_e32 v158, 16, v173
	v_and_b32_e32 v159, 0xffff0000, v173
	v_pk_mul_f32 v[156:157], v[92:93], v[156:157]
	v_pk_mul_f32 v[158:159], v[94:95], v[158:159]
	v_lshlrev_b32_e32 v244, 16, v174
	v_and_b32_e32 v245, 0xffff0000, v174
	v_lshlrev_b32_e32 v246, 16, v175
	v_and_b32_e32 v247, 0xffff0000, v175
	v_pk_mul_f32 v[244:245], v[88:89], v[244:245]
	v_pk_mul_f32 v[246:247], v[90:91], v[246:247]
	v_lshlrev_b32_e32 v196, 16, v176
	v_and_b32_e32 v197, 0xffff0000, v176
	v_lshlrev_b32_e32 v198, 16, v177
	v_and_b32_e32 v199, 0xffff0000, v177
	v_pk_add_f32 v[156:157], v[156:157], v[196:197]
	v_pk_add_f32 v[158:159], v[158:159], v[198:199]
	v_lshlrev_b32_e32 v200, 16, v178
	v_and_b32_e32 v201, 0xffff0000, v178
	v_lshlrev_b32_e32 v204, 16, v179
	v_and_b32_e32 v205, 0xffff0000, v179
	v_pk_add_f32 v[244:245], v[244:245], v[200:201]
	v_pk_add_f32 v[246:247], v[246:247], v[204:205]
	v_cvt_pk_bf16_f32 v228, v156, v157
	v_cvt_pk_bf16_f32 v229, v158, v159
	v_cvt_pk_bf16_f32 v230, v244, v245
	v_cvt_pk_bf16_f32 v231, v246, v247
	s_nop 3
	v_permlane32_swap_b32_e32 v228, v230
	v_permlane32_swap_b32_e32 v229, v231
	s_nop 3
	v_permlane16_swap_b32_e32 v228, v230
	v_permlane16_swap_b32_e32 v229, v231
	s_nop 3
	global_store_dwordx4 v163, v[228:231], s[6:7] offset:256
	v_add_u32_e32 v147, 0x1a000, v160
	global_load_dwordx4 v[172:175], v147, s[0:1]
	v_add_u32_e32 v210, 0x90000, v163
	global_load_dwordx4 v[176:179], v210, s[6:7] offset:256
	s_waitcnt vmcnt(21)
; __device__ __forceinline__ float bflo(unsigned u) { return __uint_as_float(u << 16); }
; __device__ __forceinline__ float bfhi(unsigned u) { return __uint_as_float(u & 0xFFFF0000u); }
; __device__ __forceinline__ void phaseE(const Params& p, int layer) {
;     ...
;               uint4 g4[2]; uint2 old[2][2];
; #pragma unroll
;               for (int mm = 0; mm < 2; mm++) {
;                 const int m = mh * 2 + mm;
;                 g4[mm] = *(const uint4*)(gsb + ((ai * 2 + bj) * 4 + m) * 8192 + gs_lane);
;                 if (br) {
; #pragma unroll
;                   for (int n = 0; n < 2; n++)
;                     old[mm][n] = *(const uint2*)(mb + ((size_t)(ai * 128 + m * 16) * 2048 + bj * 128 + n * 16) * 2 + lane_m);
;                 }
;               }
; #pragma unroll
;               for (int mm = 0; mm < 2; mm++) {
;                 const int m = mh * 2 + mm;
;                 const unsigned gq[4] = {g4[mm].x, g4[mm].y, g4[mm].z, g4[mm].w};
; #pragma unroll
;                 for (int n = 0; n < 2; n++) {
;                   f32x4 v = acc[ai][bj][m][n];
;                   float o0 = bflo(gq[2 * n]) * v[0], o1 = bfhi(gq[2 * n]) * v[1], o2 = bflo(gq[2 * n + 1]) * v[2], o3 = bfhi(gq[2 * n + 1]) * v[3];
;                   char* mp = mb + ((size_t)(ai * 128 + m * 16) * 2048 + bj * 128 + n * 16) * 2 + lane_m;
;                   if (br) { o0 += bflo(old[mm][n].x); o1 += bfhi(old[mm][n].x); o2 += bflo(old[mm][n].y); o3 += bfhi(old[mm][n].y); }
;                   *(uint2*)mp = make_uint2(pk2(o0, o1), pk2(o2, o3));
;                 }
;               }
	s_nop 3
	v_permlane16_swap_b32_e32 v184, v186
	v_permlane16_swap_b32_e32 v185, v187
	s_nop 3
	v_permlane32_swap_b32_e32 v184, v186
	v_permlane32_swap_b32_e32 v185, v187
	s_nop 3
	v_lshlrev_b32_e32 v156, 16, v180
	v_and_b32_e32 v157, 0xffff0000, v180
	v_lshlrev_b32_e32 v158, 16, v181
	v_and_b32_e32 v159, 0xffff0000, v181
	v_pk_mul_f32 v[156:157], v[84:85], v[156:157]
	v_pk_mul_f32 v[158:159], v[86:87], v[158:159]
	v_lshlrev_b32_e32 v244, 16, v182
	v_and_b32_e32 v245, 0xffff0000, v182
	v_lshlrev_b32_e32 v246, 16, v183
	v_and_b32_e32 v247, 0xffff0000, v183
	v_pk_mul_f32 v[244:245], v[80:81], v[244:245]
	v_pk_mul_f32 v[246:247], v[82:83], v[246:247]
	v_lshlrev_b32_e32 v196, 16, v184
	v_and_b32_e32 v197, 0xffff0000, v184
	v_lshlrev_b32_e32 v198, 16, v185
	v_and_b32_e32 v199, 0xffff0000, v185
	v_pk_add_f32 v[156:157], v[156:157], v[196:197]
	v_pk_add_f32 v[158:159], v[158:159], v[198:199]
	v_lshlrev_b32_e32 v200, 16, v186
	v_and_b32_e32 v201, 0xffff0000, v186
	v_lshlrev_b32_e32 v204, 16, v187
	v_and_b32_e32 v205, 0xffff0000, v187
	v_pk_add_f32 v[244:245], v[244:245], v[200:201]
	v_pk_add_f32 v[246:247], v[246:247], v[204:205]
	v_cvt_pk_bf16_f32 v232, v156, v157
	v_cvt_pk_bf16_f32 v233, v158, v159
	v_cvt_pk_bf16_f32 v234, v244, v245
	v_cvt_pk_bf16_f32 v235, v246, v247
	v_add_u32_e32 v211, 0x10000, v163
	s_nop 3
	v_permlane32_swap_b32_e32 v232, v234
	v_permlane32_swap_b32_e32 v233, v235
	s_nop 3
	v_permlane16_swap_b32_e32 v232, v234
	v_permlane16_swap_b32_e32 v233, v235
	s_nop 3
	global_store_dwordx4 v211, v[232:235], s[6:7] offset:256
	v_add_u32_e32 v146, 0x1c000, v160
	global_load_dwordx4 v[180:183], v146, s[0:1]
	v_add_u32_e32 v210, 0xa0000, v163
	global_load_dwordx4 v[184:187], v210, s[6:7] offset:256
	s_waitcnt vmcnt(22)
	s_nop 3
	v_permlane16_swap_b32_e32 v192, v194
	v_permlane16_swap_b32_e32 v193, v195
	s_nop 3
	v_permlane32_swap_b32_e32 v192, v194
	v_permlane32_swap_b32_e32 v193, v195
	s_nop 3
	v_lshlrev_b32_e32 v156, 16, v188
	v_and_b32_e32 v157, 0xffff0000, v188
	v_lshlrev_b32_e32 v158, 16, v189
	v_and_b32_e32 v159, 0xffff0000, v189
	v_pk_mul_f32 v[156:157], v[76:77], v[156:157]
	v_pk_mul_f32 v[158:159], v[78:79], v[158:159]
	v_lshlrev_b32_e32 v244, 16, v190
	v_and_b32_e32 v245, 0xffff0000, v190
	v_lshlrev_b32_e32 v246, 16, v191
	v_and_b32_e32 v247, 0xffff0000, v191
	v_pk_mul_f32 v[244:245], v[72:73], v[244:245]
	v_pk_mul_f32 v[246:247], v[74:75], v[246:247]
	v_lshlrev_b32_e32 v196, 16, v192
	v_and_b32_e32 v197, 0xffff0000, v192
	v_lshlrev_b32_e32 v198, 16, v193
	v_and_b32_e32 v199, 0xffff0000, v193
	v_pk_add_f32 v[156:157], v[156:157], v[196:197]
	v_pk_add_f32 v[158:159], v[158:159], v[198:199]
	v_lshlrev_b32_e32 v200, 16, v194
	v_and_b32_e32 v201, 0xffff0000, v194
	v_lshlrev_b32_e32 v204, 16, v195
	v_and_b32_e32 v205, 0xffff0000, v195
	v_pk_add_f32 v[244:245], v[244:245], v[200:201]
	v_pk_add_f32 v[246:247], v[246:247], v[204:205]
	v_cvt_pk_bf16_f32 v236, v156, v157
	v_cvt_pk_bf16_f32 v237, v158, v159
	v_cvt_pk_bf16_f32 v238, v244, v245
	v_cvt_pk_bf16_f32 v239, v246, v247
	v_add_u32_e32 v211, 0x20000, v163
	s_nop 3
	v_permlane32_swap_b32_e32 v236, v238
	v_permlane32_swap_b32_e32 v237, v239
	s_nop 3
	v_permlane16_swap_b32_e32 v236, v238
	v_permlane16_swap_b32_e32 v237, v239
	s_nop 3
	global_store_dwordx4 v211, v[236:239], s[6:7] offset:256
	v_add_u32_e32 v147, 0x1e000, v160
	global_load_dwordx4 v[188:191], v147, s[0:1]
	v_add_u32_e32 v210, 0xb0000, v163
	global_load_dwordx4 v[192:195], v210, s[6:7] offset:256
	s_waitcnt vmcnt(23)
	s_nop 3
	v_permlane16_swap_b32_e32 v216, v218
	v_permlane16_swap_b32_e32 v217, v219
	s_nop 3
	v_permlane32_swap_b32_e32 v216, v218
	v_permlane32_swap_b32_e32 v217, v219
	s_nop 3
	v_lshlrev_b32_e32 v156, 16, v212
	v_and_b32_e32 v157, 0xffff0000, v212
	v_lshlrev_b32_e32 v158, 16, v213
	v_and_b32_e32 v159, 0xffff0000, v213
	v_pk_mul_f32 v[156:157], v[68:69], v[156:157]
	v_pk_mul_f32 v[158:159], v[70:71], v[158:159]
	v_lshlrev_b32_e32 v244, 16, v214
	v_and_b32_e32 v245, 0xffff0000, v214
	v_lshlrev_b32_e32 v246, 16, v215
	v_and_b32_e32 v247, 0xffff0000, v215
	v_pk_mul_f32 v[244:245], v[64:65], v[244:245]
	v_pk_mul_f32 v[246:247], v[66:67], v[246:247]
	v_lshlrev_b32_e32 v196, 16, v216
	v_and_b32_e32 v197, 0xffff0000, v216
	v_lshlrev_b32_e32 v198, 16, v217
	v_and_b32_e32 v199, 0xffff0000, v217
	v_pk_add_f32 v[156:157], v[156:157], v[196:197]
	v_pk_add_f32 v[158:159], v[158:159], v[198:199]
	v_lshlrev_b32_e32 v200, 16, v218
	v_and_b32_e32 v201, 0xffff0000, v218
	v_lshlrev_b32_e32 v204, 16, v219
	v_and_b32_e32 v205, 0xffff0000, v219
	v_pk_add_f32 v[244:245], v[244:245], v[200:201]
	v_pk_add_f32 v[246:247], v[246:247], v[204:205]
	v_cvt_pk_bf16_f32 v240, v156, v157
	v_cvt_pk_bf16_f32 v241, v158, v159
	v_cvt_pk_bf16_f32 v242, v244, v245
	v_cvt_pk_bf16_f32 v243, v246, v247
	v_add_u32_e32 v211, 0x30000, v163
	s_nop 3
	v_permlane32_swap_b32_e32 v240, v242
	v_permlane32_swap_b32_e32 v241, v243
	s_nop 3
	v_permlane16_swap_b32_e32 v240, v242
	v_permlane16_swap_b32_e32 v241, v243
	s_nop 3
	global_store_dwordx4 v211, v[240:243], s[6:7] offset:256
	s_waitcnt vmcnt(22)
; __device__ __forceinline__ float bflo(unsigned u) { return __uint_as_float(u << 16); }
; __device__ __forceinline__ float bfhi(unsigned u) { return __uint_as_float(u & 0xFFFF0000u); }
; __device__ __forceinline__ void phaseE(const Params& p, int layer) {
;     ...
;               uint4 g4[2]; uint2 old[2][2];
; #pragma unroll
;               for (int mm = 0; mm < 2; mm++) {
;                 const int m = mh * 2 + mm;
;                 g4[mm] = *(const uint4*)(gsb + ((ai * 2 + bj) * 4 + m) * 8192 + gs_lane);
;                 if (br) {
; #pragma unroll
;                   for (int n = 0; n < 2; n++)
;                     old[mm][n] = *(const uint2*)(mb + ((size_t)(ai * 128 + m * 16) * 2048 + bj * 128 + n * 16) * 2 + lane_m);
;                 }
;               }
; #pragma unroll
;               for (int mm = 0; mm < 2; mm++) {
;                 const int m = mh * 2 + mm;
;                 const unsigned gq[4] = {g4[mm].x, g4[mm].y, g4[mm].z, g4[mm].w};
; #pragma unroll
;                 for (int n = 0; n < 2; n++) {
;                   f32x4 v = acc[ai][bj][m][n];
;                   float o0 = bflo(gq[2 * n]) * v[0], o1 = bfhi(gq[2 * n]) * v[1], o2 = bflo(gq[2 * n + 1]) * v[2], o3 = bfhi(gq[2 * n + 1]) * v[3];
;                   char* mp = mb + ((size_t)(ai * 128 + m * 16) * 2048 + bj * 128 + n * 16) * 2 + lane_m;
;                   if (br) { o0 += bflo(old[mm][n].x); o1 += bfhi(old[mm][n].x); o2 += bflo(old[mm][n].y); o3 += bfhi(old[mm][n].y); }
;                   *(uint2*)mp = make_uint2(pk2(o0, o1), pk2(o2, o3));
;                 }
;               }
	s_nop 3
	v_permlane16_swap_b32_e32 v224, v226
	v_permlane16_swap_b32_e32 v225, v227
	s_nop 3
	v_permlane32_swap_b32_e32 v224, v226
	v_permlane32_swap_b32_e32 v225, v227
	s_nop 3
	v_lshlrev_b32_e32 v156, 16, v220
	v_and_b32_e32 v157, 0xffff0000, v220
	v_lshlrev_b32_e32 v158, 16, v221
	v_and_b32_e32 v159, 0xffff0000, v221
	v_pk_mul_f32 v[156:157], v[60:61], v[156:157]
	v_pk_mul_f32 v[158:159], v[62:63], v[158:159]
	v_lshlrev_b32_e32 v244, 16, v222
	v_and_b32_e32 v245, 0xffff0000, v222
	v_lshlrev_b32_e32 v246, 16, v223
	v_and_b32_e32 v247, 0xffff0000, v223
	v_pk_mul_f32 v[244:245], v[56:57], v[244:245]
	v_pk_mul_f32 v[246:247], v[58:59], v[246:247]
	v_lshlrev_b32_e32 v196, 16, v224
	v_and_b32_e32 v197, 0xffff0000, v224
	v_lshlrev_b32_e32 v198, 16, v225
	v_and_b32_e32 v199, 0xffff0000, v225
	v_pk_add_f32 v[156:157], v[156:157], v[196:197]
	v_pk_add_f32 v[158:159], v[158:159], v[198:199]
	v_lshlrev_b32_e32 v200, 16, v226
	v_and_b32_e32 v201, 0xffff0000, v226
	v_lshlrev_b32_e32 v204, 16, v227
	v_and_b32_e32 v205, 0xffff0000, v227
	v_pk_add_f32 v[244:245], v[244:245], v[200:201]
	v_pk_add_f32 v[246:247], v[246:247], v[204:205]
	v_cvt_pk_bf16_f32 v228, v156, v157
	v_cvt_pk_bf16_f32 v229, v158, v159
	v_cvt_pk_bf16_f32 v230, v244, v245
	v_cvt_pk_bf16_f32 v231, v246, v247
	v_add_u32_e32 v210, 0x80000, v163
	s_nop 3
	v_permlane32_swap_b32_e32 v228, v230
	v_permlane32_swap_b32_e32 v229, v231
	s_nop 3
	v_permlane16_swap_b32_e32 v228, v230
	v_permlane16_swap_b32_e32 v229, v231
	s_nop 3
	global_store_dwordx4 v210, v[228:231], s[6:7]
	s_waitcnt vmcnt(20)
	s_nop 3
	v_permlane16_swap_b32_e32 v132, v134
	v_permlane16_swap_b32_e32 v133, v135
	s_nop 3
	v_permlane32_swap_b32_e32 v132, v134
	v_permlane32_swap_b32_e32 v133, v135
	s_nop 3
	v_lshlrev_b32_e32 v156, 16, v128
	v_and_b32_e32 v157, 0xffff0000, v128
	v_lshlrev_b32_e32 v158, 16, v129
	v_and_b32_e32 v159, 0xffff0000, v129
	v_pk_mul_f32 v[156:157], v[52:53], v[156:157]
	v_pk_mul_f32 v[158:159], v[54:55], v[158:159]
	v_lshlrev_b32_e32 v244, 16, v130
	v_and_b32_e32 v245, 0xffff0000, v130
	v_lshlrev_b32_e32 v246, 16, v131
	v_and_b32_e32 v247, 0xffff0000, v131
	v_pk_mul_f32 v[244:245], v[48:49], v[244:245]
	v_pk_mul_f32 v[246:247], v[50:51], v[246:247]
	v_lshlrev_b32_e32 v196, 16, v132
	v_and_b32_e32 v197, 0xffff0000, v132
	v_lshlrev_b32_e32 v198, 16, v133
	v_and_b32_e32 v199, 0xffff0000, v133
	v_pk_add_f32 v[156:157], v[156:157], v[196:197]
	v_pk_add_f32 v[158:159], v[158:159], v[198:199]
	v_lshlrev_b32_e32 v200, 16, v134
	v_and_b32_e32 v201, 0xffff0000, v134
	v_lshlrev_b32_e32 v204, 16, v135
	v_and_b32_e32 v205, 0xffff0000, v135
	v_pk_add_f32 v[244:245], v[244:245], v[200:201]
	v_pk_add_f32 v[246:247], v[246:247], v[204:205]
	v_cvt_pk_bf16_f32 v232, v156, v157
	v_cvt_pk_bf16_f32 v233, v158, v159
	v_cvt_pk_bf16_f32 v234, v244, v245
	v_cvt_pk_bf16_f32 v235, v246, v247
	v_add_u32_e32 v211, 0x90000, v163
	s_nop 3
	v_permlane32_swap_b32_e32 v232, v234
	v_permlane32_swap_b32_e32 v233, v235
	s_nop 3
	v_permlane16_swap_b32_e32 v232, v234
	v_permlane16_swap_b32_e32 v233, v235
	s_nop 3
	global_store_dwordx4 v211, v[232:235], s[6:7]
	s_waitcnt vmcnt(18)
	s_nop 3
	v_permlane16_swap_b32_e32 v140, v142
	v_permlane16_swap_b32_e32 v141, v143
	s_nop 3
	v_permlane32_swap_b32_e32 v140, v142
	v_permlane32_swap_b32_e32 v141, v143
	s_nop 3
	v_lshlrev_b32_e32 v156, 16, v136
	v_and_b32_e32 v157, 0xffff0000, v136
	v_lshlrev_b32_e32 v158, 16, v137
	v_and_b32_e32 v159, 0xffff0000, v137
	v_pk_mul_f32 v[156:157], v[44:45], v[156:157]
	v_pk_mul_f32 v[158:159], v[46:47], v[158:159]
	v_lshlrev_b32_e32 v244, 16, v138
	v_and_b32_e32 v245, 0xffff0000, v138
	v_lshlrev_b32_e32 v246, 16, v139
	v_and_b32_e32 v247, 0xffff0000, v139
	v_pk_mul_f32 v[244:245], v[40:41], v[244:245]
	v_pk_mul_f32 v[246:247], v[42:43], v[246:247]
	v_lshlrev_b32_e32 v196, 16, v140
	v_and_b32_e32 v197, 0xffff0000, v140
	v_lshlrev_b32_e32 v198, 16, v141
	v_and_b32_e32 v199, 0xffff0000, v141
	v_pk_add_f32 v[156:157], v[156:157], v[196:197]
	v_pk_add_f32 v[158:159], v[158:159], v[198:199]
	v_lshlrev_b32_e32 v200, 16, v142
	v_and_b32_e32 v201, 0xffff0000, v142
	v_lshlrev_b32_e32 v204, 16, v143
	v_and_b32_e32 v205, 0xffff0000, v143
	v_pk_add_f32 v[244:245], v[244:245], v[200:201]
	v_pk_add_f32 v[246:247], v[246:247], v[204:205]
	v_cvt_pk_bf16_f32 v236, v156, v157
	v_cvt_pk_bf16_f32 v237, v158, v159
	v_cvt_pk_bf16_f32 v238, v244, v245
	v_cvt_pk_bf16_f32 v239, v246, v247
	v_add_u32_e32 v210, 0xa0000, v163
	s_nop 3
	v_permlane32_swap_b32_e32 v236, v238
	v_permlane32_swap_b32_e32 v237, v239
	s_nop 3
	v_permlane16_swap_b32_e32 v236, v238
	v_permlane16_swap_b32_e32 v237, v239
	s_nop 3
	global_store_dwordx4 v210, v[236:239], s[6:7]
	s_waitcnt vmcnt(16)
	s_nop 3
	v_permlane16_swap_b32_e32 v152, v154
	v_permlane16_swap_b32_e32 v153, v155
	s_nop 3
	v_permlane32_swap_b32_e32 v152, v154
	v_permlane32_swap_b32_e32 v153, v155
	s_nop 3
	v_lshlrev_b32_e32 v156, 16, v148
	v_and_b32_e32 v157, 0xffff0000, v148
	v_lshlrev_b32_e32 v158, 16, v149
	v_and_b32_e32 v159, 0xffff0000, v149
	v_pk_mul_f32 v[156:157], v[36:37], v[156:157]
	v_pk_mul_f32 v[158:159], v[38:39], v[158:159]
	v_lshlrev_b32_e32 v244, 16, v150
	v_and_b32_e32 v245, 0xffff0000, v150
	v_lshlrev_b32_e32 v246, 16, v151
	v_and_b32_e32 v247, 0xffff0000, v151
	v_pk_mul_f32 v[244:245], v[32:33], v[244:245]
	v_pk_mul_f32 v[246:247], v[34:35], v[246:247]
	v_lshlrev_b32_e32 v196, 16, v152
	v_and_b32_e32 v197, 0xffff0000, v152
	v_lshlrev_b32_e32 v198, 16, v153
	v_and_b32_e32 v199, 0xffff0000, v153
	v_pk_add_f32 v[156:157], v[156:157], v[196:197]
	v_pk_add_f32 v[158:159], v[158:159], v[198:199]
	v_lshlrev_b32_e32 v200, 16, v154
	v_and_b32_e32 v201, 0xffff0000, v154
	v_lshlrev_b32_e32 v204, 16, v155
	v_and_b32_e32 v205, 0xffff0000, v155
	v_pk_add_f32 v[244:245], v[244:245], v[200:201]
	v_pk_add_f32 v[246:247], v[246:247], v[204:205]
	v_cvt_pk_bf16_f32 v240, v156, v157
	v_cvt_pk_bf16_f32 v241, v158, v159
	v_cvt_pk_bf16_f32 v242, v244, v245
	v_cvt_pk_bf16_f32 v243, v246, v247
	v_add_u32_e32 v211, 0xb0000, v163
	s_nop 3
	v_permlane32_swap_b32_e32 v240, v242
	v_permlane32_swap_b32_e32 v241, v243
	s_nop 3
	v_permlane16_swap_b32_e32 v240, v242
	v_permlane16_swap_b32_e32 v241, v243
	s_nop 3
	global_store_dwordx4 v211, v[240:243], s[6:7]
	s_waitcnt vmcnt(14)
; __device__ __forceinline__ float bflo(unsigned u) { return __uint_as_float(u << 16); }
; __device__ __forceinline__ float bfhi(unsigned u) { return __uint_as_float(u & 0xFFFF0000u); }
; __device__ __forceinline__ void phaseE(const Params& p, int layer) {
;     ...
;               uint4 g4[2]; uint2 old[2][2];
; #pragma unroll
;               for (int mm = 0; mm < 2; mm++) {
;                 const int m = mh * 2 + mm;
;                 g4[mm] = *(const uint4*)(gsb + ((ai * 2 + bj) * 4 + m) * 8192 + gs_lane);
;                 if (br) {
; #pragma unroll
;                   for (int n = 0; n < 2; n++)
;                     old[mm][n] = *(const uint2*)(mb + ((size_t)(ai * 128 + m * 16) * 2048 + bj * 128 + n * 16) * 2 + lane_m);
;                 }
;               }
; #pragma unroll
;               for (int mm = 0; mm < 2; mm++) {
;                 const int m = mh * 2 + mm;
;                 const unsigned gq[4] = {g4[mm].x, g4[mm].y, g4[mm].z, g4[mm].w};
; #pragma unroll
;                 for (int n = 0; n < 2; n++) {
;                   f32x4 v = acc[ai][bj][m][n];
;                   float o0 = bflo(gq[2 * n]) * v[0], o1 = bfhi(gq[2 * n]) * v[1], o2 = bflo(gq[2 * n + 1]) * v[2], o3 = bfhi(gq[2 * n + 1]) * v[3];
;                   char* mp = mb + ((size_t)(ai * 128 + m * 16) * 2048 + bj * 128 + n * 16) * 2 + lane_m;
;                   if (br) { o0 += bflo(old[mm][n].x); o1 += bfhi(old[mm][n].x); o2 += bflo(old[mm][n].y); o3 += bfhi(old[mm][n].y); }
;                   *(uint2*)mp = make_uint2(pk2(o0, o1), pk2(o2, o3));
;                 }
;               }
	s_nop 3
	v_permlane16_swap_b32_e32 v168, v170
	v_permlane16_swap_b32_e32 v169, v171
	s_nop 3
	v_permlane32_swap_b32_e32 v168, v170
	v_permlane32_swap_b32_e32 v169, v171
	s_nop 3
	v_lshlrev_b32_e32 v156, 16, v164
	v_and_b32_e32 v157, 0xffff0000, v164
	v_lshlrev_b32_e32 v158, 16, v165
	v_and_b32_e32 v159, 0xffff0000, v165
	v_pk_mul_f32 v[156:157], v[28:29], v[156:157]
	v_pk_mul_f32 v[158:159], v[30:31], v[158:159]
	v_lshlrev_b32_e32 v244, 16, v166
	v_and_b32_e32 v245, 0xffff0000, v166
	v_lshlrev_b32_e32 v246, 16, v167
	v_and_b32_e32 v247, 0xffff0000, v167
	v_pk_mul_f32 v[244:245], v[24:25], v[244:245]
	v_pk_mul_f32 v[246:247], v[26:27], v[246:247]
	v_lshlrev_b32_e32 v196, 16, v168
	v_and_b32_e32 v197, 0xffff0000, v168
	v_lshlrev_b32_e32 v198, 16, v169
	v_and_b32_e32 v199, 0xffff0000, v169
	v_pk_add_f32 v[156:157], v[156:157], v[196:197]
	v_pk_add_f32 v[158:159], v[158:159], v[198:199]
	v_lshlrev_b32_e32 v200, 16, v170
	v_and_b32_e32 v201, 0xffff0000, v170
	v_lshlrev_b32_e32 v204, 16, v171
	v_and_b32_e32 v205, 0xffff0000, v171
	v_pk_add_f32 v[244:245], v[244:245], v[200:201]
	v_pk_add_f32 v[246:247], v[246:247], v[204:205]
	v_cvt_pk_bf16_f32 v228, v156, v157
	v_cvt_pk_bf16_f32 v229, v158, v159
	v_cvt_pk_bf16_f32 v230, v244, v245
	v_cvt_pk_bf16_f32 v231, v246, v247
	v_add_u32_e32 v210, 0x80000, v163
	s_nop 3
	v_permlane32_swap_b32_e32 v228, v230
	v_permlane32_swap_b32_e32 v229, v231
	s_nop 3
	v_permlane16_swap_b32_e32 v228, v230
	v_permlane16_swap_b32_e32 v229, v231
	s_nop 3
	global_store_dwordx4 v210, v[228:231], s[6:7] offset:256
	s_waitcnt vmcnt(12)
	s_nop 3
	v_permlane16_swap_b32_e32 v176, v178
	v_permlane16_swap_b32_e32 v177, v179
	s_nop 3
	v_permlane32_swap_b32_e32 v176, v178
	v_permlane32_swap_b32_e32 v177, v179
	s_nop 3
	v_lshlrev_b32_e32 v156, 16, v172
	v_and_b32_e32 v157, 0xffff0000, v172
	v_lshlrev_b32_e32 v158, 16, v173
	v_and_b32_e32 v159, 0xffff0000, v173
	v_pk_mul_f32 v[156:157], v[20:21], v[156:157]
	v_pk_mul_f32 v[158:159], v[22:23], v[158:159]
	v_lshlrev_b32_e32 v244, 16, v174
	v_and_b32_e32 v245, 0xffff0000, v174
	v_lshlrev_b32_e32 v246, 16, v175
	v_and_b32_e32 v247, 0xffff0000, v175
	v_pk_mul_f32 v[244:245], v[16:17], v[244:245]
	v_pk_mul_f32 v[246:247], v[18:19], v[246:247]
	v_lshlrev_b32_e32 v196, 16, v176
	v_and_b32_e32 v197, 0xffff0000, v176
	v_lshlrev_b32_e32 v198, 16, v177
	v_and_b32_e32 v199, 0xffff0000, v177
	v_pk_add_f32 v[156:157], v[156:157], v[196:197]
	v_pk_add_f32 v[158:159], v[158:159], v[198:199]
	v_lshlrev_b32_e32 v200, 16, v178
	v_and_b32_e32 v201, 0xffff0000, v178
	v_lshlrev_b32_e32 v204, 16, v179
	v_and_b32_e32 v205, 0xffff0000, v179
	v_pk_add_f32 v[244:245], v[244:245], v[200:201]
	v_pk_add_f32 v[246:247], v[246:247], v[204:205]
	v_cvt_pk_bf16_f32 v232, v156, v157
	v_cvt_pk_bf16_f32 v233, v158, v159
	v_cvt_pk_bf16_f32 v234, v244, v245
	v_cvt_pk_bf16_f32 v235, v246, v247
	v_add_u32_e32 v211, 0x90000, v163
	s_nop 3
	v_permlane32_swap_b32_e32 v232, v234
	v_permlane32_swap_b32_e32 v233, v235
	s_nop 3
	v_permlane16_swap_b32_e32 v232, v234
	v_permlane16_swap_b32_e32 v233, v235
	s_nop 3
	global_store_dwordx4 v211, v[232:235], s[6:7] offset:256
	s_waitcnt vmcnt(10)
	s_nop 3
	v_permlane16_swap_b32_e32 v184, v186
	v_permlane16_swap_b32_e32 v185, v187
	s_nop 3
	v_permlane32_swap_b32_e32 v184, v186
	v_permlane32_swap_b32_e32 v185, v187
	s_nop 3
	v_lshlrev_b32_e32 v156, 16, v180
	v_and_b32_e32 v157, 0xffff0000, v180
	v_lshlrev_b32_e32 v158, 16, v181
	v_and_b32_e32 v159, 0xffff0000, v181
	v_pk_mul_f32 v[156:157], v[12:13], v[156:157]
	v_pk_mul_f32 v[158:159], v[14:15], v[158:159]
	v_lshlrev_b32_e32 v244, 16, v182
	v_and_b32_e32 v245, 0xffff0000, v182
	v_lshlrev_b32_e32 v246, 16, v183
	v_and_b32_e32 v247, 0xffff0000, v183
	v_pk_mul_f32 v[244:245], v[8:9], v[244:245]
	v_pk_mul_f32 v[246:247], v[10:11], v[246:247]
	v_lshlrev_b32_e32 v196, 16, v184
	v_and_b32_e32 v197, 0xffff0000, v184
	v_lshlrev_b32_e32 v198, 16, v185
	v_and_b32_e32 v199, 0xffff0000, v185
	v_pk_add_f32 v[156:157], v[156:157], v[196:197]
	v_pk_add_f32 v[158:159], v[158:159], v[198:199]
	v_lshlrev_b32_e32 v200, 16, v186
	v_and_b32_e32 v201, 0xffff0000, v186
	v_lshlrev_b32_e32 v204, 16, v187
	v_and_b32_e32 v205, 0xffff0000, v187
	v_pk_add_f32 v[244:245], v[244:245], v[200:201]
	v_pk_add_f32 v[246:247], v[246:247], v[204:205]
	v_cvt_pk_bf16_f32 v236, v156, v157
	v_cvt_pk_bf16_f32 v237, v158, v159
	v_cvt_pk_bf16_f32 v238, v244, v245
	v_cvt_pk_bf16_f32 v239, v246, v247
	v_add_u32_e32 v210, 0xa0000, v163
	s_nop 3
	v_permlane32_swap_b32_e32 v236, v238
	v_permlane32_swap_b32_e32 v237, v239
	s_nop 3
	v_permlane16_swap_b32_e32 v236, v238
	v_permlane16_swap_b32_e32 v237, v239
	s_nop 3
	global_store_dwordx4 v210, v[236:239], s[6:7] offset:256
	s_waitcnt vmcnt(8)
	s_nop 3
	v_permlane16_swap_b32_e32 v192, v194
	v_permlane16_swap_b32_e32 v193, v195
	s_nop 3
	v_permlane32_swap_b32_e32 v192, v194
	v_permlane32_swap_b32_e32 v193, v195
	s_nop 3
	v_lshlrev_b32_e32 v156, 16, v188
	v_and_b32_e32 v157, 0xffff0000, v188
	v_lshlrev_b32_e32 v158, 16, v189
	v_and_b32_e32 v159, 0xffff0000, v189
	v_pk_mul_f32 v[156:157], v[4:5], v[156:157]
	v_pk_mul_f32 v[158:159], v[6:7], v[158:159]
	v_lshlrev_b32_e32 v244, 16, v190
	v_and_b32_e32 v245, 0xffff0000, v190
	v_lshlrev_b32_e32 v246, 16, v191
	v_and_b32_e32 v247, 0xffff0000, v191
	v_pk_mul_f32 v[244:245], v[0:1], v[244:245]
	v_pk_mul_f32 v[246:247], v[2:3], v[246:247]
	v_lshlrev_b32_e32 v196, 16, v192
	v_and_b32_e32 v197, 0xffff0000, v192
	v_lshlrev_b32_e32 v198, 16, v193
	v_and_b32_e32 v199, 0xffff0000, v193
	v_pk_add_f32 v[156:157], v[156:157], v[196:197]
	v_pk_add_f32 v[158:159], v[158:159], v[198:199]
	v_lshlrev_b32_e32 v200, 16, v194
	v_and_b32_e32 v201, 0xffff0000, v194
	v_lshlrev_b32_e32 v204, 16, v195
	v_and_b32_e32 v205, 0xffff0000, v195
	v_pk_add_f32 v[244:245], v[244:245], v[200:201]
	v_pk_add_f32 v[246:247], v[246:247], v[204:205]
	v_cvt_pk_bf16_f32 v240, v156, v157
	v_cvt_pk_bf16_f32 v241, v158, v159
	v_cvt_pk_bf16_f32 v242, v244, v245
	v_cvt_pk_bf16_f32 v243, v246, v247
	v_add_u32_e32 v211, 0xb0000, v163
	s_nop 3
	v_permlane32_swap_b32_e32 v240, v242
	v_permlane32_swap_b32_e32 v241, v243
	s_nop 3
	v_permlane16_swap_b32_e32 v240, v242
	v_permlane16_swap_b32_e32 v241, v243
	s_nop 3
	global_store_dwordx4 v211, v[240:243], s[6:7] offset:256
	s_branch .LBB0_2313
; __device__ __forceinline__ float bflo(unsigned u) { return __uint_as_float(u << 16); }
; __device__ __forceinline__ float bfhi(unsigned u) { return __uint_as_float(u & 0xFFFF0000u); }
; __device__ __forceinline__ void phaseE(const Params& p, int layer) {
;     ...
;               uint4 g4[2]; uint2 old[2][2];
; #pragma unroll
;               for (int mm = 0; mm < 2; mm++) {
;                 const int m = mh * 2 + mm;
;                 g4[mm] = *(const uint4*)(gsb + ((ai * 2 + bj) * 4 + m) * 8192 + gs_lane);
;                 if (br) {
; #pragma unroll
;                   for (int n = 0; n < 2; n++)
;                     old[mm][n] = *(const uint2*)(mb + ((size_t)(ai * 128 + m * 16) * 2048 + bj * 128 + n * 16) * 2 + lane_m);
;                 }
;               }
; #pragma unroll
;               for (int mm = 0; mm < 2; mm++) {
;                 const int m = mh * 2 + mm;
;                 const unsigned gq[4] = {g4[mm].x, g4[mm].y, g4[mm].z, g4[mm].w};
; #pragma unroll
;                 for (int n = 0; n < 2; n++) {
;                   f32x4 v = acc[ai][bj][m][n];
;                   float o0 = bflo(gq[2 * n]) * v[0], o1 = bfhi(gq[2 * n]) * v[1], o2 = bflo(gq[2 * n + 1]) * v[2], o3 = bfhi(gq[2 * n + 1]) * v[3];
;                   char* mp = mb + ((size_t)(ai * 128 + m * 16) * 2048 + bj * 128 + n * 16) * 2 + lane_m;
;                   if (br) { o0 += bflo(old[mm][n].x); o1 += bfhi(old[mm][n].x); o2 += bflo(old[mm][n].y); o3 += bfhi(old[mm][n].y); }
;                   *(uint2*)mp = make_uint2(pk2(o0, o1), pk2(o2, o3));
;                 }
;               }
.Lbrepi_first:
	ds_read_b128 v[128:131], v165
	ds_read_b128 v[136:139], v165 offset:8192
	ds_read_b128 v[148:151], v165 offset:16384
	ds_read_b128 v[164:167], v165 offset:24576
	v_add_u32_e32 v146, 0x8000, v160
	global_load_dwordx4 v[172:175], v146, s[0:1]
	v_add_u32_e32 v147, 0xa000, v160
	global_load_dwordx4 v[180:183], v147, s[0:1]
	v_add_u32_e32 v146, 0xc000, v160
	global_load_dwordx4 v[188:191], v146, s[0:1]
	v_add_u32_e32 v147, 0xe000, v160
	global_load_dwordx4 v[212:215], v147, s[0:1]
	v_add_u32_e32 v146, 0x10000, v160
	global_load_dwordx4 v[220:223], v146, s[0:1]
	s_waitcnt lgkmcnt(0)
	v_lshlrev_b32_e32 v156, 16, v128
	v_and_b32_e32 v157, 0xffff0000, v128
	v_lshlrev_b32_e32 v158, 16, v129
	v_and_b32_e32 v159, 0xffff0000, v129
	v_pk_mul_f32 v[156:157], v[124:125], v[156:157]
	v_pk_mul_f32 v[158:159], v[126:127], v[158:159]
	v_lshlrev_b32_e32 v244, 16, v130
	v_and_b32_e32 v245, 0xffff0000, v130
	v_lshlrev_b32_e32 v246, 16, v131
	v_and_b32_e32 v247, 0xffff0000, v131
	v_pk_mul_f32 v[244:245], v[120:121], v[244:245]
	v_pk_mul_f32 v[246:247], v[122:123], v[246:247]
	v_cvt_pk_bf16_f32 v228, v156, v157
	v_cvt_pk_bf16_f32 v229, v158, v159
	v_cvt_pk_bf16_f32 v230, v244, v245
	v_cvt_pk_bf16_f32 v231, v246, v247
	s_nop 3
	v_permlane32_swap_b32_e32 v228, v230
	v_permlane32_swap_b32_e32 v229, v231
	s_nop 3
	v_permlane16_swap_b32_e32 v228, v230
	v_permlane16_swap_b32_e32 v229, v231
	s_nop 3
	global_store_dwordx4 v163, v[228:231], s[6:7]
	v_add_u32_e32 v147, 0x12000, v160
	global_load_dwordx4 v[128:131], v147, s[0:1]
	s_waitcnt lgkmcnt(0)
	v_lshlrev_b32_e32 v156, 16, v136
	v_and_b32_e32 v157, 0xffff0000, v136
	v_lshlrev_b32_e32 v158, 16, v137
	v_and_b32_e32 v159, 0xffff0000, v137
	v_pk_mul_f32 v[156:157], v[116:117], v[156:157]
	v_pk_mul_f32 v[158:159], v[118:119], v[158:159]
	v_lshlrev_b32_e32 v244, 16, v138
	v_and_b32_e32 v245, 0xffff0000, v138
	v_lshlrev_b32_e32 v246, 16, v139
	v_and_b32_e32 v247, 0xffff0000, v139
	v_pk_mul_f32 v[244:245], v[112:113], v[244:245]
	v_pk_mul_f32 v[246:247], v[114:115], v[246:247]
	v_cvt_pk_bf16_f32 v232, v156, v157
	v_cvt_pk_bf16_f32 v233, v158, v159
	v_cvt_pk_bf16_f32 v234, v244, v245
	v_cvt_pk_bf16_f32 v235, v246, v247
	v_add_u32_e32 v210, 0x10000, v163
	s_nop 3
	v_permlane32_swap_b32_e32 v232, v234
	v_permlane32_swap_b32_e32 v233, v235
	s_nop 3
	v_permlane16_swap_b32_e32 v232, v234
	v_permlane16_swap_b32_e32 v233, v235
	s_nop 3
	global_store_dwordx4 v210, v[232:235], s[6:7]
	v_add_u32_e32 v146, 0x14000, v160
	global_load_dwordx4 v[136:139], v146, s[0:1]
	s_waitcnt lgkmcnt(0)
	v_lshlrev_b32_e32 v156, 16, v148
	v_and_b32_e32 v157, 0xffff0000, v148
	v_lshlrev_b32_e32 v158, 16, v149
	v_and_b32_e32 v159, 0xffff0000, v149
	v_pk_mul_f32 v[156:157], v[108:109], v[156:157]
	v_pk_mul_f32 v[158:159], v[110:111], v[158:159]
	v_lshlrev_b32_e32 v244, 16, v150
	v_and_b32_e32 v245, 0xffff0000, v150
	v_lshlrev_b32_e32 v246, 16, v151
	v_and_b32_e32 v247, 0xffff0000, v151
	v_pk_mul_f32 v[244:245], v[104:105], v[244:245]
	v_pk_mul_f32 v[246:247], v[106:107], v[246:247]
	v_cvt_pk_bf16_f32 v236, v156, v157
	v_cvt_pk_bf16_f32 v237, v158, v159
	v_cvt_pk_bf16_f32 v238, v244, v245
	v_cvt_pk_bf16_f32 v239, v246, v247
	v_add_u32_e32 v211, 0x20000, v163
	s_nop 3
	v_permlane32_swap_b32_e32 v236, v238
	v_permlane32_swap_b32_e32 v237, v239
	s_nop 3
	v_permlane16_swap_b32_e32 v236, v238
	v_permlane16_swap_b32_e32 v237, v239
	s_nop 3
	global_store_dwordx4 v211, v[236:239], s[6:7]
	v_add_u32_e32 v147, 0x16000, v160
	global_load_dwordx4 v[148:151], v147, s[0:1]
	s_waitcnt lgkmcnt(0)
	v_lshlrev_b32_e32 v156, 16, v164
	v_and_b32_e32 v157, 0xffff0000, v164
	v_lshlrev_b32_e32 v158, 16, v165
	v_and_b32_e32 v159, 0xffff0000, v165
	v_pk_mul_f32 v[156:157], v[100:101], v[156:157]
	v_pk_mul_f32 v[158:159], v[102:103], v[158:159]
	v_lshlrev_b32_e32 v244, 16, v166
	v_and_b32_e32 v245, 0xffff0000, v166
	v_lshlrev_b32_e32 v246, 16, v167
	v_and_b32_e32 v247, 0xffff0000, v167
	v_pk_mul_f32 v[244:245], v[96:97], v[244:245]
	v_pk_mul_f32 v[246:247], v[98:99], v[246:247]
	v_cvt_pk_bf16_f32 v240, v156, v157
	v_cvt_pk_bf16_f32 v241, v158, v159
	v_cvt_pk_bf16_f32 v242, v244, v245
	v_cvt_pk_bf16_f32 v243, v246, v247
	v_add_u32_e32 v210, 0x30000, v163
	s_nop 3
	v_permlane32_swap_b32_e32 v240, v242
	v_permlane32_swap_b32_e32 v241, v243
	s_nop 3
	v_permlane16_swap_b32_e32 v240, v242
	v_permlane16_swap_b32_e32 v241, v243
	s_nop 3
	global_store_dwordx4 v210, v[240:243], s[6:7]
	v_add_u32_e32 v146, 0x18000, v160
	global_load_dwordx4 v[164:167], v146, s[0:1]
	s_waitcnt vmcnt(12)
	v_lshlrev_b32_e32 v156, 16, v172
	v_and_b32_e32 v157, 0xffff0000, v172
	v_lshlrev_b32_e32 v158, 16, v173
	v_and_b32_e32 v159, 0xffff0000, v173
	v_pk_mul_f32 v[156:157], v[92:93], v[156:157]
	v_pk_mul_f32 v[158:159], v[94:95], v[158:159]
	v_lshlrev_b32_e32 v244, 16, v174
	v_and_b32_e32 v245, 0xffff0000, v174
	v_lshlrev_b32_e32 v246, 16, v175
	v_and_b32_e32 v247, 0xffff0000, v175
	v_pk_mul_f32 v[244:245], v[88:89], v[244:245]
	v_pk_mul_f32 v[246:247], v[90:91], v[246:247]
	v_cvt_pk_bf16_f32 v228, v156, v157
	v_cvt_pk_bf16_f32 v229, v158, v159
	v_cvt_pk_bf16_f32 v230, v244, v245
	v_cvt_pk_bf16_f32 v231, v246, v247
	s_nop 3
	v_permlane32_swap_b32_e32 v228, v230
	v_permlane32_swap_b32_e32 v229, v231
	s_nop 3
	v_permlane16_swap_b32_e32 v228, v230
	v_permlane16_swap_b32_e32 v229, v231
	s_nop 3
	global_store_dwordx4 v163, v[228:231], s[6:7] offset:256
	v_add_u32_e32 v147, 0x1a000, v160
	global_load_dwordx4 v[172:175], v147, s[0:1]
	s_waitcnt vmcnt(13)
; __device__ __forceinline__ float bflo(unsigned u) { return __uint_as_float(u << 16); }
; __device__ __forceinline__ float bfhi(unsigned u) { return __uint_as_float(u & 0xFFFF0000u); }
; __device__ __forceinline__ void phaseE(const Params& p, int layer) {
;     ...
;               uint4 g4[2]; uint2 old[2][2];
; #pragma unroll
;               for (int mm = 0; mm < 2; mm++) {
;                 const int m = mh * 2 + mm;
;                 g4[mm] = *(const uint4*)(gsb + ((ai * 2 + bj) * 4 + m) * 8192 + gs_lane);
;                 if (br) {
; #pragma unroll
;                   for (int n = 0; n < 2; n++)
;                     old[mm][n] = *(const uint2*)(mb + ((size_t)(ai * 128 + m * 16) * 2048 + bj * 128 + n * 16) * 2 + lane_m);
;                 }
;               }
; #pragma unroll
;               for (int mm = 0; mm < 2; mm++) {
;                 const int m = mh * 2 + mm;
;                 const unsigned gq[4] = {g4[mm].x, g4[mm].y, g4[mm].z, g4[mm].w};
; #pragma unroll
;                 for (int n = 0; n < 2; n++) {
;                   f32x4 v = acc[ai][bj][m][n];
;                   float o0 = bflo(gq[2 * n]) * v[0], o1 = bfhi(gq[2 * n]) * v[1], o2 = bflo(gq[2 * n + 1]) * v[2], o3 = bfhi(gq[2 * n + 1]) * v[3];
;                   char* mp = mb + ((size_t)(ai * 128 + m * 16) * 2048 + bj * 128 + n * 16) * 2 + lane_m;
;                   if (br) { o0 += bflo(old[mm][n].x); o1 += bfhi(old[mm][n].x); o2 += bflo(old[mm][n].y); o3 += bfhi(old[mm][n].y); }
;                   *(uint2*)mp = make_uint2(pk2(o0, o1), pk2(o2, o3));
;                 }
;               }
	v_lshlrev_b32_e32 v156, 16, v180
	v_and_b32_e32 v157, 0xffff0000, v180
	v_lshlrev_b32_e32 v158, 16, v181
	v_and_b32_e32 v159, 0xffff0000, v181
	v_pk_mul_f32 v[156:157], v[84:85], v[156:157]
	v_pk_mul_f32 v[158:159], v[86:87], v[158:159]
	v_lshlrev_b32_e32 v244, 16, v182
	v_and_b32_e32 v245, 0xffff0000, v182
	v_lshlrev_b32_e32 v246, 16, v183
	v_and_b32_e32 v247, 0xffff0000, v183
	v_pk_mul_f32 v[244:245], v[80:81], v[244:245]
	v_pk_mul_f32 v[246:247], v[82:83], v[246:247]
	v_cvt_pk_bf16_f32 v232, v156, v157
	v_cvt_pk_bf16_f32 v233, v158, v159
	v_cvt_pk_bf16_f32 v234, v244, v245
	v_cvt_pk_bf16_f32 v235, v246, v247
	v_add_u32_e32 v211, 0x10000, v163
	s_nop 3
	v_permlane32_swap_b32_e32 v232, v234
	v_permlane32_swap_b32_e32 v233, v235
	s_nop 3
	v_permlane16_swap_b32_e32 v232, v234
	v_permlane16_swap_b32_e32 v233, v235
	s_nop 3
	global_store_dwordx4 v211, v[232:235], s[6:7] offset:256
	v_add_u32_e32 v146, 0x1c000, v160
	global_load_dwordx4 v[180:183], v146, s[0:1]
	s_waitcnt vmcnt(14)
	v_lshlrev_b32_e32 v156, 16, v188
	v_and_b32_e32 v157, 0xffff0000, v188
	v_lshlrev_b32_e32 v158, 16, v189
	v_and_b32_e32 v159, 0xffff0000, v189
	v_pk_mul_f32 v[156:157], v[76:77], v[156:157]
	v_pk_mul_f32 v[158:159], v[78:79], v[158:159]
	v_lshlrev_b32_e32 v244, 16, v190
	v_and_b32_e32 v245, 0xffff0000, v190
	v_lshlrev_b32_e32 v246, 16, v191
	v_and_b32_e32 v247, 0xffff0000, v191
	v_pk_mul_f32 v[244:245], v[72:73], v[244:245]
	v_pk_mul_f32 v[246:247], v[74:75], v[246:247]
	v_cvt_pk_bf16_f32 v236, v156, v157
	v_cvt_pk_bf16_f32 v237, v158, v159
	v_cvt_pk_bf16_f32 v238, v244, v245
	v_cvt_pk_bf16_f32 v239, v246, v247
	v_add_u32_e32 v210, 0x20000, v163
	s_nop 3
	v_permlane32_swap_b32_e32 v236, v238
	v_permlane32_swap_b32_e32 v237, v239
	s_nop 3
	v_permlane16_swap_b32_e32 v236, v238
	v_permlane16_swap_b32_e32 v237, v239
	s_nop 3
	global_store_dwordx4 v210, v[236:239], s[6:7] offset:256
	v_add_u32_e32 v147, 0x1e000, v160
	global_load_dwordx4 v[188:191], v147, s[0:1]
	s_waitcnt vmcnt(15)
	v_lshlrev_b32_e32 v156, 16, v212
	v_and_b32_e32 v157, 0xffff0000, v212
	v_lshlrev_b32_e32 v158, 16, v213
	v_and_b32_e32 v159, 0xffff0000, v213
	v_pk_mul_f32 v[156:157], v[68:69], v[156:157]
	v_pk_mul_f32 v[158:159], v[70:71], v[158:159]
	v_lshlrev_b32_e32 v244, 16, v214
	v_and_b32_e32 v245, 0xffff0000, v214
	v_lshlrev_b32_e32 v246, 16, v215
	v_and_b32_e32 v247, 0xffff0000, v215
	v_pk_mul_f32 v[244:245], v[64:65], v[244:245]
	v_pk_mul_f32 v[246:247], v[66:67], v[246:247]
	v_cvt_pk_bf16_f32 v240, v156, v157
	v_cvt_pk_bf16_f32 v241, v158, v159
	v_cvt_pk_bf16_f32 v242, v244, v245
	v_cvt_pk_bf16_f32 v243, v246, v247
	v_add_u32_e32 v211, 0x30000, v163
	s_nop 3
	v_permlane32_swap_b32_e32 v240, v242
	v_permlane32_swap_b32_e32 v241, v243
	s_nop 3
	v_permlane16_swap_b32_e32 v240, v242
	v_permlane16_swap_b32_e32 v241, v243
	s_nop 3
	global_store_dwordx4 v211, v[240:243], s[6:7] offset:256
	s_waitcnt vmcnt(15)
	v_lshlrev_b32_e32 v156, 16, v220
	v_and_b32_e32 v157, 0xffff0000, v220
	v_lshlrev_b32_e32 v158, 16, v221
	v_and_b32_e32 v159, 0xffff0000, v221
	v_pk_mul_f32 v[156:157], v[60:61], v[156:157]
	v_pk_mul_f32 v[158:159], v[62:63], v[158:159]
	v_lshlrev_b32_e32 v244, 16, v222
	v_and_b32_e32 v245, 0xffff0000, v222
	v_lshlrev_b32_e32 v246, 16, v223
	v_and_b32_e32 v247, 0xffff0000, v223
	v_pk_mul_f32 v[244:245], v[56:57], v[244:245]
	v_pk_mul_f32 v[246:247], v[58:59], v[246:247]
	v_cvt_pk_bf16_f32 v228, v156, v157
	v_cvt_pk_bf16_f32 v229, v158, v159
	v_cvt_pk_bf16_f32 v230, v244, v245
	v_cvt_pk_bf16_f32 v231, v246, v247
	v_add_u32_e32 v210, 0x80000, v163
	s_nop 3
	v_permlane32_swap_b32_e32 v228, v230
	v_permlane32_swap_b32_e32 v229, v231
	s_nop 3
	v_permlane16_swap_b32_e32 v228, v230
	v_permlane16_swap_b32_e32 v229, v231
	s_nop 3
	global_store_dwordx4 v210, v[228:231], s[6:7]
	s_waitcnt vmcnt(14)
	v_lshlrev_b32_e32 v156, 16, v128
	v_and_b32_e32 v157, 0xffff0000, v128
	v_lshlrev_b32_e32 v158, 16, v129
	v_and_b32_e32 v159, 0xffff0000, v129
	v_pk_mul_f32 v[156:157], v[52:53], v[156:157]
	v_pk_mul_f32 v[158:159], v[54:55], v[158:159]
	v_lshlrev_b32_e32 v244, 16, v130
	v_and_b32_e32 v245, 0xffff0000, v130
	v_lshlrev_b32_e32 v246, 16, v131
	v_and_b32_e32 v247, 0xffff0000, v131
	v_pk_mul_f32 v[244:245], v[48:49], v[244:245]
	v_pk_mul_f32 v[246:247], v[50:51], v[246:247]
	v_cvt_pk_bf16_f32 v232, v156, v157
	v_cvt_pk_bf16_f32 v233, v158, v159
	v_cvt_pk_bf16_f32 v234, v244, v245
	v_cvt_pk_bf16_f32 v235, v246, v247
	v_add_u32_e32 v211, 0x90000, v163
	s_nop 3
	v_permlane32_swap_b32_e32 v232, v234
	v_permlane32_swap_b32_e32 v233, v235
	s_nop 3
	v_permlane16_swap_b32_e32 v232, v234
	v_permlane16_swap_b32_e32 v233, v235
	s_nop 3
	global_store_dwordx4 v211, v[232:235], s[6:7]
	s_waitcnt vmcnt(13)
; __device__ __forceinline__ float bflo(unsigned u) { return __uint_as_float(u << 16); }
; __device__ __forceinline__ float bfhi(unsigned u) { return __uint_as_float(u & 0xFFFF0000u); }
; __device__ __forceinline__ void phaseE(const Params& p, int layer) {
;     ...
;               uint4 g4[2]; uint2 old[2][2];
; #pragma unroll
;               for (int mm = 0; mm < 2; mm++) {
;                 const int m = mh * 2 + mm;
;                 g4[mm] = *(const uint4*)(gsb + ((ai * 2 + bj) * 4 + m) * 8192 + gs_lane);
;                 if (br) {
; #pragma unroll
;                   for (int n = 0; n < 2; n++)
;                     old[mm][n] = *(const uint2*)(mb + ((size_t)(ai * 128 + m * 16) * 2048 + bj * 128 + n * 16) * 2 + lane_m);
;                 }
;               }
; #pragma unroll
;               for (int mm = 0; mm < 2; mm++) {
;                 const int m = mh * 2 + mm;
;                 const unsigned gq[4] = {g4[mm].x, g4[mm].y, g4[mm].z, g4[mm].w};
; #pragma unroll
;                 for (int n = 0; n < 2; n++) {
;                   f32x4 v = acc[ai][bj][m][n];
;                   float o0 = bflo(gq[2 * n]) * v[0], o1 = bfhi(gq[2 * n]) * v[1], o2 = bflo(gq[2 * n + 1]) * v[2], o3 = bfhi(gq[2 * n + 1]) * v[3];
;                   char* mp = mb + ((size_t)(ai * 128 + m * 16) * 2048 + bj * 128 + n * 16) * 2 + lane_m;
;                   if (br) { o0 += bflo(old[mm][n].x); o1 += bfhi(old[mm][n].x); o2 += bflo(old[mm][n].y); o3 += bfhi(old[mm][n].y); }
;                   *(uint2*)mp = make_uint2(pk2(o0, o1), pk2(o2, o3));
;                 }
;               }
	v_lshlrev_b32_e32 v156, 16, v136
	v_and_b32_e32 v157, 0xffff0000, v136
	v_lshlrev_b32_e32 v158, 16, v137
	v_and_b32_e32 v159, 0xffff0000, v137
	v_pk_mul_f32 v[156:157], v[44:45], v[156:157]
	v_pk_mul_f32 v[158:159], v[46:47], v[158:159]
	v_lshlrev_b32_e32 v244, 16, v138
	v_and_b32_e32 v245, 0xffff0000, v138
	v_lshlrev_b32_e32 v246, 16, v139
	v_and_b32_e32 v247, 0xffff0000, v139
	v_pk_mul_f32 v[244:245], v[40:41], v[244:245]
	v_pk_mul_f32 v[246:247], v[42:43], v[246:247]
	v_cvt_pk_bf16_f32 v236, v156, v157
	v_cvt_pk_bf16_f32 v237, v158, v159
	v_cvt_pk_bf16_f32 v238, v244, v245
	v_cvt_pk_bf16_f32 v239, v246, v247
	v_add_u32_e32 v210, 0xa0000, v163
	s_nop 3
	v_permlane32_swap_b32_e32 v236, v238
	v_permlane32_swap_b32_e32 v237, v239
	s_nop 3
	v_permlane16_swap_b32_e32 v236, v238
	v_permlane16_swap_b32_e32 v237, v239
	s_nop 3
	global_store_dwordx4 v210, v[236:239], s[6:7]
	s_waitcnt vmcnt(12)
	v_lshlrev_b32_e32 v156, 16, v148
	v_and_b32_e32 v157, 0xffff0000, v148
	v_lshlrev_b32_e32 v158, 16, v149
	v_and_b32_e32 v159, 0xffff0000, v149
	v_pk_mul_f32 v[156:157], v[36:37], v[156:157]
	v_pk_mul_f32 v[158:159], v[38:39], v[158:159]
	v_lshlrev_b32_e32 v244, 16, v150
	v_and_b32_e32 v245, 0xffff0000, v150
	v_lshlrev_b32_e32 v246, 16, v151
	v_and_b32_e32 v247, 0xffff0000, v151
	v_pk_mul_f32 v[244:245], v[32:33], v[244:245]
	v_pk_mul_f32 v[246:247], v[34:35], v[246:247]
	v_cvt_pk_bf16_f32 v240, v156, v157
	v_cvt_pk_bf16_f32 v241, v158, v159
	v_cvt_pk_bf16_f32 v242, v244, v245
	v_cvt_pk_bf16_f32 v243, v246, v247
	v_add_u32_e32 v211, 0xb0000, v163
	s_nop 3
	v_permlane32_swap_b32_e32 v240, v242
	v_permlane32_swap_b32_e32 v241, v243
	s_nop 3
	v_permlane16_swap_b32_e32 v240, v242
	v_permlane16_swap_b32_e32 v241, v243
	s_nop 3
	global_store_dwordx4 v211, v[240:243], s[6:7]
	s_waitcnt vmcnt(11)
	v_lshlrev_b32_e32 v156, 16, v164
	v_and_b32_e32 v157, 0xffff0000, v164
	v_lshlrev_b32_e32 v158, 16, v165
	v_and_b32_e32 v159, 0xffff0000, v165
	v_pk_mul_f32 v[156:157], v[28:29], v[156:157]
	v_pk_mul_f32 v[158:159], v[30:31], v[158:159]
	v_lshlrev_b32_e32 v244, 16, v166
	v_and_b32_e32 v245, 0xffff0000, v166
	v_lshlrev_b32_e32 v246, 16, v167
	v_and_b32_e32 v247, 0xffff0000, v167
	v_pk_mul_f32 v[244:245], v[24:25], v[244:245]
	v_pk_mul_f32 v[246:247], v[26:27], v[246:247]
	v_cvt_pk_bf16_f32 v228, v156, v157
	v_cvt_pk_bf16_f32 v229, v158, v159
	v_cvt_pk_bf16_f32 v230, v244, v245
	v_cvt_pk_bf16_f32 v231, v246, v247
	v_add_u32_e32 v210, 0x80000, v163
	s_nop 3
	v_permlane32_swap_b32_e32 v228, v230
	v_permlane32_swap_b32_e32 v229, v231
	s_nop 3
	v_permlane16_swap_b32_e32 v228, v230
	v_permlane16_swap_b32_e32 v229, v231
	s_nop 3
	global_store_dwordx4 v210, v[228:231], s[6:7] offset:256
	s_waitcnt vmcnt(10)
	v_lshlrev_b32_e32 v156, 16, v172
	v_and_b32_e32 v157, 0xffff0000, v172
	v_lshlrev_b32_e32 v158, 16, v173
	v_and_b32_e32 v159, 0xffff0000, v173
	v_pk_mul_f32 v[156:157], v[20:21], v[156:157]
	v_pk_mul_f32 v[158:159], v[22:23], v[158:159]
	v_lshlrev_b32_e32 v244, 16, v174
	v_and_b32_e32 v245, 0xffff0000, v174
	v_lshlrev_b32_e32 v246, 16, v175
	v_and_b32_e32 v247, 0xffff0000, v175
	v_pk_mul_f32 v[244:245], v[16:17], v[244:245]
	v_pk_mul_f32 v[246:247], v[18:19], v[246:247]
	v_cvt_pk_bf16_f32 v232, v156, v157
	v_cvt_pk_bf16_f32 v233, v158, v159
	v_cvt_pk_bf16_f32 v234, v244, v245
	v_cvt_pk_bf16_f32 v235, v246, v247
	v_add_u32_e32 v211, 0x90000, v163
	s_nop 3
	v_permlane32_swap_b32_e32 v232, v234
	v_permlane32_swap_b32_e32 v233, v235
	s_nop 3
	v_permlane16_swap_b32_e32 v232, v234
	v_permlane16_swap_b32_e32 v233, v235
	s_nop 3
	global_store_dwordx4 v211, v[232:235], s[6:7] offset:256
	s_waitcnt vmcnt(9)
	v_lshlrev_b32_e32 v156, 16, v180
	v_and_b32_e32 v157, 0xffff0000, v180
	v_lshlrev_b32_e32 v158, 16, v181
	v_and_b32_e32 v159, 0xffff0000, v181
	v_pk_mul_f32 v[156:157], v[12:13], v[156:157]
	v_pk_mul_f32 v[158:159], v[14:15], v[158:159]
	v_lshlrev_b32_e32 v244, 16, v182
	v_and_b32_e32 v245, 0xffff0000, v182
	v_lshlrev_b32_e32 v246, 16, v183
	v_and_b32_e32 v247, 0xffff0000, v183
	v_pk_mul_f32 v[244:245], v[8:9], v[244:245]
	v_pk_mul_f32 v[246:247], v[10:11], v[246:247]
	v_cvt_pk_bf16_f32 v236, v156, v157
	v_cvt_pk_bf16_f32 v237, v158, v159
	v_cvt_pk_bf16_f32 v238, v244, v245
	v_cvt_pk_bf16_f32 v239, v246, v247
	v_add_u32_e32 v210, 0xa0000, v163
	s_nop 3
	v_permlane32_swap_b32_e32 v236, v238
	v_permlane32_swap_b32_e32 v237, v239
	s_nop 3
	v_permlane16_swap_b32_e32 v236, v238
	v_permlane16_swap_b32_e32 v237, v239
	s_nop 3
	global_store_dwordx4 v210, v[236:239], s[6:7] offset:256
	s_waitcnt vmcnt(8)
	v_lshlrev_b32_e32 v156, 16, v188
	v_and_b32_e32 v157, 0xffff0000, v188
	v_lshlrev_b32_e32 v158, 16, v189
	v_and_b32_e32 v159, 0xffff0000, v189
	v_pk_mul_f32 v[156:157], v[4:5], v[156:157]
	v_pk_mul_f32 v[158:159], v[6:7], v[158:159]
	v_lshlrev_b32_e32 v244, 16, v190
	v_and_b32_e32 v245, 0xffff0000, v190
	v_lshlrev_b32_e32 v246, 16, v191
	v_and_b32_e32 v247, 0xffff0000, v191
	v_pk_mul_f32 v[244:245], v[0:1], v[244:245]
	v_pk_mul_f32 v[246:247], v[2:3], v[246:247]
	v_cvt_pk_bf16_f32 v240, v156, v157
	v_cvt_pk_bf16_f32 v241, v158, v159
	v_cvt_pk_bf16_f32 v242, v244, v245
	v_cvt_pk_bf16_f32 v243, v246, v247
	v_add_u32_e32 v211, 0xb0000, v163
	s_nop 3
	v_permlane32_swap_b32_e32 v240, v242
	v_permlane32_swap_b32_e32 v241, v243
	s_nop 3
	v_permlane16_swap_b32_e32 v240, v242
	v_permlane16_swap_b32_e32 v241, v243
	s_nop 3
	global_store_dwordx4 v211, v[240:243], s[6:7] offset:256
	s_branch .LBB0_2313
